# v19a: v19 with s_nop padding where the removed row-sum swaps were (same issue-slot layout as v15)
# speedup vs baseline: 1.0034x; 1.0034x over previous
.LBB0_526:
	ds_read_b128 v[64:67], v192 offset:49152
	ds_read_b128 v[68:71], v192 offset:57344
	ds_read_b128 v[232:235], v200 offset:49152
	ds_read_b128 v[236:239], v200 offset:57344
	ds_read_b128 v[250:253], v199 offset:49152
	ds_read_b128 v[244:247], v199 offset:57344
	ds_read_b128 v[212:215], v198 offset:49152
	ds_read_b128 v[216:219], v198 offset:57344
	v_add_f32_e32 v162, v163, v177
	s_waitcnt lgkmcnt(6)
	v_mfma_f32_32x32x16_bf16 v[80:95], v[64:67], v[118:121], 0
	v_add_f32_e32 v162, v164, v162
	v_add_f32_e32 v162, v207, v162
	v_add_f32_e32 v162, v176, v162
	v_add_f32_e32 v162, v210, v162
	v_mfma_f32_32x32x16_bf16 v[64:79], v[68:71], v[118:121], 0
	v_add_f32_e32 v162, v165, v162
	v_add_f32_e32 v162, v175, v162
	v_add_f32_e32 v162, v166, v162
	v_add_f32_e32 v162, v173, v162
	v_add_f32_e32 v162, v167, v162
	s_waitcnt lgkmcnt(4)
	v_mfma_f32_32x32x16_bf16 v[80:95], v[232:235], v[114:117], v[80:95]
	ds_read_b128 v[232:235], v195 offset:49152
	v_add_f32_e32 v162, v174, v162
	v_exp_f32_e32 v160, v160
	v_add_f32_e32 v162, v168, v162
	v_exp_f32_e32 v161, v161
	v_mfma_f32_32x32x16_bf16 v[64:79], v[236:239], v[114:117], v[64:79]
	ds_read_b128 v[236:239], v195 offset:57344
	v_add_f32_e32 v162, v171, v162
	v_exp_f32_e32 v158, v158
	v_add_f32_e32 v162, v169, v162
	v_exp_f32_e32 v159, v159
	s_waitcnt lgkmcnt(4)
	v_mfma_f32_32x32x16_bf16 v[80:95], v[250:253], v[126:129], v[80:95]
	ds_read_b128 v[250:253], v193 offset:49152
	v_add_f32_e32 v162, v172, v162
	v_exp_f32_e32 v154, v154
	v_add_f32_e32 v162, v160, v162
	v_exp_f32_e32 v155, v155
	v_mfma_f32_32x32x16_bf16 v[64:79], v[244:247], v[126:129], v[64:79]
	ds_read_b128 v[244:247], v193 offset:57344
	v_add_f32_e32 v162, v161, v162
	v_exp_f32_e32 v150, v150
	v_add_f32_e32 v162, v158, v162
	v_exp_f32_e32 v151, v151
	s_waitcnt lgkmcnt(4)
	v_mfma_f32_32x32x16_bf16 v[80:95], v[212:215], v[122:125], v[80:95]
	ds_read_b128 v[212:215], v202 offset:49152
	v_add_f32_e32 v162, v159, v162
	v_exp_f32_e32 v148, v148
	v_add_f32_e32 v162, v154, v162
	v_exp_f32_e32 v149, v149
	v_mfma_f32_32x32x16_bf16 v[64:79], v[216:219], v[122:125], v[64:79]
	ds_read_b128 v[216:219], v202 offset:57344
	v_add_f32_e32 v162, v155, v162
	v_exp_f32_e32 v156, v156
	v_add_f32_e32 v162, v150, v162
	v_exp_f32_e32 v157, v157
	s_waitcnt lgkmcnt(4)
	v_mfma_f32_32x32x16_bf16 v[80:95], v[232:235], v[110:113], v[80:95]
	ds_read_b128 v[232:235], v201 offset:49152
	v_add_f32_e32 v162, v151, v162
	v_exp_f32_e32 v152, v152
	v_add_f32_e32 v162, v148, v162
	v_exp_f32_e32 v153, v153
	v_mfma_f32_32x32x16_bf16 v[64:79], v[236:239], v[110:113], v[64:79]
	ds_read_b128 v[236:239], v201 offset:57344
	v_add_f32_e32 v162, v149, v162
	v_exp_f32_e32 v146, v146
	v_add_f32_e32 v162, v156, v162
	v_exp_f32_e32 v147, v147
	s_waitcnt lgkmcnt(4)
	v_mfma_f32_32x32x16_bf16 v[80:95], v[250:253], v[106:109], v[80:95]
	v_add_f32_e32 v162, v157, v162
	v_add_f32_e32 v162, v152, v162
	v_add_f32_e32 v162, v153, v162
	v_add_f32_e32 v162, v146, v162
	v_add_f32_e32 v204, v147, v162
	v_fma_f32 v185, v203, v185, v204
	v_mfma_f32_32x32x16_bf16 v[64:79], v[244:247], v[106:109], v[64:79]
	s_nop 0
	s_nop 0
	v_cvt_pk_bf16_f32 v162, v163, v177
	v_cvt_pk_bf16_f32 v163, v164, v207
	v_cvt_pk_bf16_f32 v164, v176, v210
	s_waitcnt lgkmcnt(2)
	v_mfma_f32_32x32x16_bf16 v[80:95], v[212:215], v[102:105], v[80:95]
	v_cvt_pk_bf16_f32 v165, v165, v175
	v_cvt_pk_bf16_f32 v166, v166, v173
	v_cvt_pk_bf16_f32 v167, v167, v174
	v_cvt_pk_bf16_f32 v168, v168, v171
	v_mfma_f32_32x32x16_bf16 v[64:79], v[216:219], v[102:105], v[64:79]
	v_cvt_pk_bf16_f32 v169, v169, v172
	v_cvt_pk_bf16_f32 v172, v160, v161
	v_cvt_pk_bf16_f32 v173, v158, v159
	v_cvt_pk_bf16_f32 v174, v154, v155
	ds_read_b64_tr_b16 v[210:211], v187 offset:0x0
	ds_read_b64_tr_b16 v[212:213], v187 offset:0x800
	ds_read_b64_tr_b16 v[214:215], v187 offset:0x200
	ds_read_b64_tr_b16 v[216:217], v187 offset:0xa00
	ds_read_b64_tr_b16 v[218:219], v187 offset:0x400
	ds_read_b64_tr_b16 v[220:221], v187 offset:0xc00
	ds_read_b64_tr_b16 v[222:223], v187 offset:0x600
	ds_read_b64_tr_b16 v[224:225], v187 offset:0xe00
	s_waitcnt lgkmcnt(8)
	v_mfma_f32_32x32x16_bf16 v[80:95], v[232:235], v[98:101], v[80:95]
	v_cvt_pk_bf16_f32 v175, v150, v151
	v_cvt_pk_bf16_f32 v206, v148, v149
	v_cvt_pk_bf16_f32 v207, v156, v157
	v_mfma_f32_32x32x16_bf16 v[64:79], v[236:239], v[98:101], v[64:79]
	v_cvt_pk_bf16_f32 v208, v152, v153
	v_cvt_pk_bf16_f32 v209, v146, v147
	s_waitcnt vmcnt(0)
	ds_write_b128 v188, v[134:137] offset:32768
	ds_write_b128 v189, v[142:145] offset:32768
	global_load_dwordx4 v[146:149], v178, s[66:67]
	global_load_dwordx4 v[150:153], v179, s[66:67]
	global_load_dwordx4 v[154:157], v178, s[98:99]
	global_load_dwordx4 v[158:161], v179, s[98:99]
	s_add_u32 s66, s66, 0x4000
	s_addc_u32 s67, s67, 0
	s_add_u32 s98, s98, 0x4000
	s_addc_u32 s99, s99, 0
	s_waitcnt lgkmcnt(6)
	v_mfma_f32_32x32x16_bf16 v[0:15], v[162:165], v[210:213], v[0:15]
	ds_read_b64_tr_b16 v[210:211], v187 offset:0x1000
	ds_read_b64_tr_b16 v[212:213], v187 offset:0x1800
	v_max_f32_e32 v240, v80, v81
	v_max3_f32 v240, v240, v82, v83
	v_max3_f32 v240, v240, v84, v85
	v_max3_f32 v240, v240, v86, v87
	v_max3_f32 v240, v240, v88, v89
	v_mfma_f32_32x32x16_bf16 v[48:63], v[162:165], v[214:217], v[48:63]
	ds_read_b64_tr_b16 v[214:215], v187 offset:0x1200
	ds_read_b64_tr_b16 v[216:217], v187 offset:0x1a00
	v_max3_f32 v240, v240, v90, v91
	v_max3_f32 v240, v240, v92, v93
	v_max3_f32 v240, v240, v94, v95
	v_max3_f32 v240, v240, v64, v65
	v_max3_f32 v240, v240, v66, v67
	v_max3_f32 v240, v240, v68, v69
	s_waitcnt lgkmcnt(6)
	v_mfma_f32_32x32x16_bf16 v[32:47], v[162:165], v[218:221], v[32:47]
	ds_read_b64_tr_b16 v[218:219], v187 offset:0x1400
	ds_read_b64_tr_b16 v[220:221], v187 offset:0x1c00
	v_max3_f32 v240, v240, v70, v71
	v_max3_f32 v240, v240, v72, v73
	v_max3_f32 v240, v240, v74, v75
	v_max3_f32 v240, v240, v76, v77
	v_max3_f32 v240, v240, v78, v79
	v_mfma_f32_32x32x16_bf16 v[16:31], v[162:165], v[222:225], v[16:31]
	ds_read_b64_tr_b16 v[222:223], v187 offset:0x1600
	ds_read_b64_tr_b16 v[224:225], v187 offset:0x1e00
	v_mov_b32_e32 v241, v240
	s_nop 1
	v_permlane32_swap_b32_e32 v240, v241
	v_max_f32_e32 v240, v240, v241
	v_sub_f32_e32 v241, v240, v243
	v_cmp_ge_f32_e32 vcc, s92, v241
	s_waitcnt lgkmcnt(4)
	v_mfma_f32_32x32x16_bf16 v[0:15], v[166:169], v[210:213], v[0:15]
	ds_read_b64_tr_b16 v[210:211], v187 offset:0x2000
	ds_read_b64_tr_b16 v[212:213], v187 offset:0x2800
	s_cmp_eq_u64 vcc, exec
	s_cselect_b64 s[42:43], -1, 0
	s_cbranch_scc1 .Lattn_common_a
	v_max_f32_e32 v240, v243, v240
	v_sub_f32_e32 v241, v243, v240
	v_mul_f32_e32 v241, 0x3e0293ee, v241
	v_exp_f32_e32 v241, v241
	v_mov_b32_e32 v243, v240
	v_mul_f32_e32 v242, 0xbe0293ee, v243

.LBB0_530:
	v_fmamk_f32 v217, v64, 0x3e0293ee, v242
	v_fmamk_f32 v218, v65, 0x3e0293ee, v242
	v_fmamk_f32 v219, v66, 0x3e0293ee, v242
	v_fmamk_f32 v220, v67, 0x3e0293ee, v242
	v_fmamk_f32 v221, v68, 0x3e0293ee, v242
	v_fmamk_f32 v210, v69, 0x3e0293ee, v242
	v_fmamk_f32 v211, v70, 0x3e0293ee, v242
	v_fmamk_f32 v212, v71, 0x3e0293ee, v242
	v_fmamk_f32 v213, v72, 0x3e0293ee, v242
	v_fmamk_f32 v214, v73, 0x3e0293ee, v242
	v_fmamk_f32 v215, v74, 0x3e0293ee, v242
	v_fmamk_f32 v216, v75, 0x3e0293ee, v242
	v_fmamk_f32 v209, v76, 0x3e0293ee, v242
	v_fmamk_f32 v222, v77, 0x3e0293ee, v242
	v_fmamk_f32 v223, v78, 0x3e0293ee, v242
	v_fmamk_f32 v208, v79, 0x3e0293ee, v242
	s_waitcnt lgkmcnt(0)
	s_barrier
	ds_read_b128 v[64:67], v192 offset:32768
	ds_read_b128 v[68:71], v192 offset:40960
	ds_read_b128 v[232:235], v200 offset:32768
	ds_read_b128 v[236:239], v200 offset:40960
	ds_read_b128 v[250:253], v199 offset:32768
	ds_read_b128 v[244:247], v199 offset:40960
	ds_read_b128 v[224:227], v198 offset:32768
	ds_read_b128 v[228:231], v198 offset:40960
	v_exp_f32_e32 v248, v208
	v_exp_f32_e32 v249, v209
	s_waitcnt lgkmcnt(6)
	v_mfma_f32_32x32x16_bf16 v[80:95], v[64:67], v[118:121], 0
	v_exp_f32_e32 v217, v217
	v_add_f32_e32 v208, v162, v177
	v_exp_f32_e32 v218, v218
	v_mfma_f32_32x32x16_bf16 v[64:79], v[68:71], v[118:121], 0
	v_add_f32_e32 v208, v163, v208
	v_exp_f32_e32 v219, v219
	v_add_f32_e32 v208, v176, v208
	v_exp_f32_e32 v220, v220
	v_add_f32_e32 v208, v164, v208
	s_waitcnt lgkmcnt(4)
	v_mfma_f32_32x32x16_bf16 v[80:95], v[232:235], v[114:117], v[80:95]
	ds_read_b128 v[232:235], v195 offset:32768
	v_exp_f32_e32 v221, v221
	v_add_f32_e32 v208, v175, v208
	v_exp_f32_e32 v210, v210
	v_add_f32_e32 v208, v165, v208
	v_mfma_f32_32x32x16_bf16 v[64:79], v[236:239], v[114:117], v[64:79]
	ds_read_b128 v[236:239], v195 offset:40960
	v_exp_f32_e32 v211, v211
	v_add_f32_e32 v208, v174, v208
	v_exp_f32_e32 v212, v212
	v_add_f32_e32 v208, v166, v208
	s_waitcnt lgkmcnt(4)
	v_mfma_f32_32x32x16_bf16 v[80:95], v[250:253], v[126:129], v[80:95]
	ds_read_b128 v[250:253], v193 offset:32768
	v_exp_f32_e32 v213, v213
	v_add_f32_e32 v208, v173, v208
	v_exp_f32_e32 v214, v214
	v_add_f32_e32 v208, v167, v208
	v_mfma_f32_32x32x16_bf16 v[64:79], v[244:247], v[126:129], v[64:79]
	ds_read_b128 v[244:247], v193 offset:40960
	v_exp_f32_e32 v215, v215
	v_add_f32_e32 v208, v172, v208
	v_exp_f32_e32 v216, v216
	v_add_f32_e32 v208, v168, v208
	s_waitcnt lgkmcnt(4)
	v_mfma_f32_32x32x16_bf16 v[80:95], v[224:227], v[122:125], v[80:95]
	ds_read_b128 v[224:227], v202 offset:32768
	v_exp_f32_e32 v222, v222
	v_add_f32_e32 v208, v171, v208
	v_exp_f32_e32 v223, v223
	v_add_f32_e32 v208, v169, v208
	v_mfma_f32_32x32x16_bf16 v[64:79], v[228:231], v[122:125], v[64:79]
	ds_read_b128 v[228:231], v202 offset:40960
	v_add_f32_e32 v208, v170, v208
	v_add_f32_e32 v208, v217, v208
	v_add_f32_e32 v208, v218, v208
	v_add_f32_e32 v208, v219, v208
	s_waitcnt lgkmcnt(4)
	v_mfma_f32_32x32x16_bf16 v[80:95], v[232:235], v[110:113], v[80:95]
	ds_read_b128 v[232:235], v201 offset:32768
	v_add_f32_e32 v208, v220, v208
	v_add_f32_e32 v208, v221, v208
	v_add_f32_e32 v208, v210, v208
	v_add_f32_e32 v208, v211, v208
	v_mfma_f32_32x32x16_bf16 v[64:79], v[236:239], v[110:113], v[64:79]
	ds_read_b128 v[236:239], v201 offset:40960
	v_add_f32_e32 v208, v212, v208
	v_add_f32_e32 v208, v213, v208
	v_add_f32_e32 v208, v214, v208
	v_add_f32_e32 v208, v215, v208
	s_waitcnt lgkmcnt(4)
	v_mfma_f32_32x32x16_bf16 v[80:95], v[250:253], v[106:109], v[80:95]
	v_add_f32_e32 v208, v216, v208
	v_add_f32_e32 v208, v249, v208
	v_add_f32_e32 v208, v222, v208
	v_add_f32_e32 v208, v223, v208
	v_mfma_f32_32x32x16_bf16 v[64:79], v[244:247], v[106:109], v[64:79]
	v_add_f32_e32 v208, v248, v208
	v_fma_f32 v185, v185, v206, v208
	v_cvt_pk_bf16_f32 v162, v162, v177
	v_cvt_pk_bf16_f32 v163, v163, v176
	s_waitcnt lgkmcnt(2)
	v_mfma_f32_32x32x16_bf16 v[80:95], v[224:227], v[102:105], v[80:95]
	v_cvt_pk_bf16_f32 v164, v164, v175
	v_cvt_pk_bf16_f32 v165, v165, v174
	v_cvt_pk_bf16_f32 v166, v166, v173
	v_cvt_pk_bf16_f32 v167, v167, v172
	v_mfma_f32_32x32x16_bf16 v[64:79], v[228:231], v[102:105], v[64:79]
	v_cvt_pk_bf16_f32 v168, v168, v171
	v_cvt_pk_bf16_f32 v169, v169, v170
	v_cvt_pk_bf16_f32 v170, v217, v218
	v_cvt_pk_bf16_f32 v171, v219, v220
	s_waitcnt lgkmcnt(0)
	v_mfma_f32_32x32x16_bf16 v[80:95], v[232:235], v[98:101], v[80:95]
	v_cvt_pk_bf16_f32 v172, v221, v210
	v_cvt_pk_bf16_f32 v173, v211, v212
	v_cvt_pk_bf16_f32 v174, v213, v214
	v_cvt_pk_bf16_f32 v175, v215, v216
	v_mfma_f32_32x32x16_bf16 v[64:79], v[236:239], v[98:101], v[64:79]
	v_cvt_pk_bf16_f32 v176, v249, v222
	v_cvt_pk_bf16_f32 v177, v223, v248
	ds_read_b64_tr_b16 v[210:211], v186 offset:0x0
	ds_read_b64_tr_b16 v[212:213], v186 offset:0x800
	ds_read_b64_tr_b16 v[214:215], v186 offset:0x200
	ds_read_b64_tr_b16 v[216:217], v186 offset:0xa00
	ds_read_b64_tr_b16 v[218:219], v186 offset:0x400
	ds_read_b64_tr_b16 v[220:221], v186 offset:0xc00
	ds_read_b64_tr_b16 v[222:223], v186 offset:0x600
	ds_read_b64_tr_b16 v[224:225], v186 offset:0xe00
	s_nop 1
	s_nop 0
	s_waitcnt vmcnt(1)
	ds_write_b128 v188, v[154:157] offset:49152
	s_waitcnt vmcnt(0)
	ds_write_b128 v189, v[158:161] offset:49152
	s_cmp_ge_u32 s34, s35
	s_cselect_b64 s[6:7], -1, 0
	s_cbranch_scc1 .LBB0_532
	global_load_dwordx4 v[130:133], v178, s[66:67]
	global_load_dwordx4 v[134:137], v178, s[98:99]
	global_load_dwordx4 v[138:141], v179, s[66:67]
	global_load_dwordx4 v[142:145], v179, s[98:99]
	s_add_u32 s66, s66, 0x4000
	s_addc_u32 s67, s67, 0
	s_add_u32 s98, s98, 0x4000
	s_addc_u32 s99, s99, 0
